# move last 512 Affo conversion items from P2 into P1 idle-slot workgroups
# speedup vs baseline: 1.0017x; 1.0017x over previous
.LBB0_270:
	s_cmpk_lt_i32 s2, 0xe0
	s_cbranch_scc1 .LBB0_365
	s_lshl_b32 s0, s2, 3
	v_readlane_b32 s1, v245, 49
	s_add_i32 s1, s1, s0
	s_addk_i32 s1, 0xf900
	s_cmpk_gt_i32 s1, 0x57f
	s_cbranch_scc1 .LBB0_365
	s_add_i32 s10, s1, 0x1280
	s_cmpk_gt_i32 s1, 0xf0ff
	s_cbranch_scc0 .LBB0_277
	s_cmpk_gt_u32 s10, 0x57f
	s_cbranch_scc0 .LBB0_278
	s_cmpk_gt_u32 s10, 0x77f
	s_cbranch_scc0 .LBB0_279
	s_cmp_lt_u32 s1, 0xffffed80
	s_cbranch_scc0 .LBB0_280
	s_lshl_b32 s0, s1, 1
	s_lshl_b32 s4, s10, 5
	s_and_b32 s0, s0, 0x1ffc0
	s_and_b32 s8, s4, 0x3e0
	v_readlane_b32 s36, v245, 50
	s_add_u32 s4, s34, 0x1400000
	v_readlane_b32 s48, v245, 62
	v_readlane_b32 s49, v245, 63
	s_addc_u32 s5, s35, 0
	s_mov_b64 s[30:31], 0
	s_mov_b64 s[6:7], 0
	v_readlane_b32 s37, v245, 51
	v_readlane_b32 s38, v245, 52
	v_readlane_b32 s39, v245, 53
	v_readlane_b32 s40, v245, 54
	v_readlane_b32 s41, v245, 55
	v_readlane_b32 s42, v245, 56
	v_readlane_b32 s43, v245, 57
	v_readlane_b32 s44, v245, 58
	v_readlane_b32 s45, v245, 59
	v_readlane_b32 s46, v245, 60
	v_readlane_b32 s47, v245, 61
	v_readlane_b32 s50, v244, 0
	v_readlane_b32 s51, v244, 1
	s_mov_b64 s[28:29], s[48:49]
	s_branch .LBB0_281

.LBB0_307:
	s_cmpk_lt_i32 s10, 0x1700
	s_cselect_b64 s[72:73], -1, 0
	s_cmpk_gt_i32 s10, 0x16ff
	s_cbranch_scc1 .LBB0_333
	s_add_i32 s1, s10, 0x100
	s_cmpk_gt_i32 s10, 0x27f
	s_cbranch_scc0 .LBB0_314
	s_cmpk_gt_u32 s1, 0x57f
	s_mov_b64 s[36:37], -1
	s_cbranch_scc0 .LBB0_318
	s_cmpk_gt_u32 s1, 0x77f
	s_cbranch_scc0 .LBB0_315
	s_cmpk_gt_u32 s1, 0x127f
	s_cbranch_scc0 .LBB0_343
	s_lshl_b32 s11, s10, 1
	s_add_i32 s11, s11, 0x1dd00
	v_readlane_b32 s44, v245, 50
	s_and_b32 s68, s11, 0x1ffc0
	s_lshl_b32 s11, s1, 5
	v_readlane_b32 s56, v245, 62
	v_readlane_b32 s57, v245, 63
	s_and_b32 s11, s11, 0x3e0
	s_mov_b64 s[74:75], 0
	v_readlane_b32 s45, v245, 51
	v_readlane_b32 s46, v245, 52
	v_readlane_b32 s47, v245, 53
	v_readlane_b32 s48, v245, 54
	v_readlane_b32 s49, v245, 55
	v_readlane_b32 s50, v245, 56
	v_readlane_b32 s51, v245, 57
	v_readlane_b32 s52, v245, 58
	v_readlane_b32 s53, v245, 59
	v_readlane_b32 s54, v245, 60
	v_readlane_b32 s55, v245, 61
	v_readlane_b32 s58, v244, 0
	v_readlane_b32 s59, v244, 1
	s_mov_b64 s[28:29], s[56:57]
	s_cbranch_execz .LBB0_344
	s_mov_b64 s[80:81], 0x400
	s_movk_i32 s33, 0xb00
	s_movk_i32 s16, 0x400
	s_mov_b32 s30, s11
	s_mov_b64 s[70:71], s[38:39]
	s_cbranch_execz .LBB0_316
	s_branch .LBB0_317

.LBB0_333:
	s_waitcnt vmcnt(7)
	v_mul_f32_e32 v4, v101, v10
	s_waitcnt vmcnt(1)
	v_pk_mul_f32 v[104:105], v[28:29], v[4:5] op_sel_hi:[1,0]
	v_pk_mul_f32 v[4:5], v[26:27], v[4:5] op_sel_hi:[1,0]
	ds_write2_b32 v100, v4, v5 offset1:1
	ds_write2_b32 v100, v104, v105 offset0:2 offset1:3
	v_mul_f32_e32 v4, v101, v1
	s_waitcnt vmcnt(0)
	v_pk_mul_f32 v[106:107], v[32:33], v[4:5] op_sel_hi:[1,0]
	v_pk_mul_f32 v[4:5], v[30:31], v[4:5] op_sel_hi:[1,0]
	v_add_u32_e32 v103, 0x420, v100
	ds_write2_b32 v103, v4, v5 offset1:1
	v_mul_f32_e32 v4, v101, v12
	v_pk_mul_f32 v[108:109], v[36:37], v[4:5] op_sel_hi:[1,0]
	v_pk_mul_f32 v[4:5], v[34:35], v[4:5] op_sel_hi:[1,0]
	v_add_u32_e32 v105, 0x840, v100
	v_add_u32_e32 v104, 0x428, v100
	ds_write2_b32 v105, v4, v5 offset1:1
	v_mul_f32_e32 v4, v101, v11
	ds_write2_b32 v104, v106, v107 offset1:1
	v_pk_mul_f32 v[110:111], v[40:41], v[4:5] op_sel_hi:[1,0]
	v_pk_mul_f32 v[4:5], v[38:39], v[4:5] op_sel_hi:[1,0]
	v_add_u32_e32 v107, 0xc60, v100
	v_add_u32_e32 v106, 0x848, v100
	ds_write2_b32 v107, v4, v5 offset1:1
	v_mul_f32_e32 v4, v101, v14
	ds_write2_b32 v106, v108, v109 offset1:1
	v_pk_mul_f32 v[112:113], v[44:45], v[4:5] op_sel_hi:[1,0]
	v_pk_mul_f32 v[4:5], v[42:43], v[4:5] op_sel_hi:[1,0]
	v_add_u32_e32 v109, 0x1080, v100
	v_add_u32_e32 v108, 0xc68, v100
	ds_write2_b32 v109, v4, v5 offset1:1
	v_mul_f32_e32 v4, v101, v15
	ds_write2_b32 v108, v110, v111 offset1:1
	v_pk_mul_f32 v[114:115], v[48:49], v[4:5] op_sel_hi:[1,0]
	v_pk_mul_f32 v[4:5], v[46:47], v[4:5] op_sel_hi:[1,0]
	v_add_u32_e32 v111, 0x14a0, v100
	v_add_u32_e32 v110, 0x1088, v100
	ds_write2_b32 v111, v4, v5 offset1:1
	v_mul_f32_e32 v4, v101, v16
	ds_write2_b32 v110, v112, v113 offset1:1
	v_add_u32_e32 v112, 0x14a8, v100
	v_pk_mul_f32 v[116:117], v[52:53], v[4:5] op_sel_hi:[1,0]
	v_pk_mul_f32 v[4:5], v[50:51], v[4:5] op_sel_hi:[1,0]
	v_add_u32_e32 v113, 0x18c0, v100
	ds_write2_b32 v112, v114, v115 offset1:1
	ds_write2_b32 v113, v4, v5 offset1:1
	v_add_u32_e32 v114, 0x18c8, v100
	v_mul_f32_e32 v4, v101, v13
	ds_write2_b32 v114, v116, v117 offset1:1
	v_pk_mul_f32 v[118:119], v[56:57], v[4:5] op_sel_hi:[1,0]
	v_pk_mul_f32 v[4:5], v[54:55], v[4:5] op_sel_hi:[1,0]
	v_add_u32_e32 v115, 0x1ce0, v100
	v_add_u32_e32 v116, 0x1ce8, v100
	ds_write2_b32 v115, v4, v5 offset1:1
	ds_write2_b32 v116, v118, v119 offset1:1
	s_waitcnt lgkmcnt(0)
	v_add_u32_e32 v3, s8, v17
	ds_read2_b32 v[4:5], v98 offset0:33 offset1:41
	ds_read2_b32 v[122:123], v98 offset1:8
	ds_read2_b32 v[124:125], v98 offset0:66 offset1:74
	ds_read2_b32 v[126:127], v98 offset0:99 offset1:107
	ds_read2_b32 v[128:129], v98 offset0:132 offset1:140
	ds_read2_b32 v[130:131], v98 offset0:165 offset1:173
	ds_read2_b32 v[132:133], v98 offset0:198 offset1:206
	ds_read2_b32 v[134:135], v98 offset0:231 offset1:239
	v_mad_u64_u32 v[136:137], s[16:17], s9, v3, 0
	s_waitcnt lgkmcnt(6)
	v_cvt_pk_bf16_f32 v118, v122, v4
	v_ashrrev_i32_e32 v87, 31, v3
	v_mov_b32_e32 v4, v137
	v_mad_u64_u32 v[138:139], s[16:17], s9, v87, v[4:5]
	v_mov_b32_e32 v137, v138
	s_ashr_i32 s1, s0, 31
	v_lshl_add_u64 v[136:137], v[136:137], 1, s[4:5]
	s_lshl_b64 s[16:17], s[0:1], 1
	v_lshl_add_u64 v[136:137], v[136:137], 0, s[16:17]
	v_mov_b32_e32 v89, v2
	s_waitcnt lgkmcnt(4)
	v_cvt_pk_bf16_f32 v119, v124, v126
	s_waitcnt lgkmcnt(2)
	v_cvt_pk_bf16_f32 v120, v128, v130
	s_waitcnt lgkmcnt(0)
	v_cvt_pk_bf16_f32 v121, v132, v134
	v_lshl_add_u64 v[136:137], v[136:137], 0, v[88:89]
	v_add_u32_e32 v3, s8, v91
	global_store_dwordx4 v[136:137], v[118:121], off
	v_ashrrev_i32_e32 v87, 31, v3
	s_andn2_b64 vcc, exec, s[72:73]
	v_cvt_pk_bf16_f32 v118, v123, v5
	v_mad_u64_u32 v[4:5], s[18:19], s9, v3, 0
	v_mov_b32_e32 v122, v5
	v_mad_u64_u32 v[122:123], s[18:19], s9, v87, v[122:123]
	v_mov_b32_e32 v5, v122
	v_lshl_add_u64 v[4:5], v[4:5], 1, s[4:5]
	v_lshl_add_u64 v[4:5], v[4:5], 0, s[16:17]
	v_cvt_pk_bf16_f32 v119, v125, v127
	v_cvt_pk_bf16_f32 v120, v129, v131
	v_cvt_pk_bf16_f32 v121, v133, v135
	v_lshl_add_u64 v[4:5], v[4:5], 0, v[88:89]
	v_add_u32_e32 v3, s8, v92
	ds_read2_b32 v[122:123], v98 offset0:16 offset1:24
	ds_read2_b32 v[124:125], v98 offset0:49 offset1:57
	ds_read2_b32 v[126:127], v98 offset0:82 offset1:90
	ds_read2_b32 v[128:129], v98 offset0:115 offset1:123
	ds_read2_b32 v[130:131], v98 offset0:148 offset1:156
	ds_read2_b32 v[132:133], v98 offset0:181 offset1:189
	ds_read2_b32 v[134:135], v98 offset0:214 offset1:222
	ds_read2_b32 v[136:137], v98 offset0:247 offset1:255
	global_store_dwordx4 v[4:5], v[118:121], off
	v_mad_u64_u32 v[4:5], s[18:19], s9, v3, 0
	s_waitcnt lgkmcnt(6)
	v_cvt_pk_bf16_f32 v118, v122, v124
	v_ashrrev_i32_e32 v87, 31, v3
	v_mov_b32_e32 v122, v5
	v_mad_u64_u32 v[138:139], s[18:19], s9, v87, v[122:123]
	v_mov_b32_e32 v5, v138
	v_lshl_add_u64 v[4:5], v[4:5], 1, s[4:5]
	v_lshl_add_u64 v[4:5], v[4:5], 0, s[16:17]
	s_waitcnt lgkmcnt(4)
	v_cvt_pk_bf16_f32 v119, v126, v128
	s_waitcnt lgkmcnt(2)
	v_cvt_pk_bf16_f32 v120, v130, v132
	s_waitcnt lgkmcnt(0)
	v_cvt_pk_bf16_f32 v121, v134, v136
	v_lshl_add_u64 v[4:5], v[4:5], 0, v[88:89]
	v_add_u32_e32 v3, s8, v93
	global_store_dwordx4 v[4:5], v[118:121], off
	v_mad_u64_u32 v[4:5], s[18:19], s9, v3, 0
	v_ashrrev_i32_e32 v87, 31, v3
	v_mov_b32_e32 v122, v5
	v_cvt_pk_bf16_f32 v118, v123, v125
	v_mad_u64_u32 v[122:123], s[18:19], s9, v87, v[122:123]
	v_mov_b32_e32 v5, v122
	v_lshl_add_u64 v[4:5], v[4:5], 1, s[4:5]
	v_lshl_add_u64 v[4:5], v[4:5], 0, s[16:17]
	v_cvt_pk_bf16_f32 v119, v127, v129
	v_cvt_pk_bf16_f32 v120, v131, v133
	v_cvt_pk_bf16_f32 v121, v135, v137
	v_lshl_add_u64 v[4:5], v[4:5], 0, v[88:89]
	global_store_dwordx4 v[4:5], v[118:121], off
	s_waitcnt lgkmcnt(0)
	s_mov_b64 s[72:73], 0
	s_cbranch_vccnz .LBB0_306
	s_add_i32 s1, s10, 0x200
	s_cmpk_lt_i32 s10, 0x1600
	s_cselect_b64 s[72:73], -1, 0
	s_cmpk_gt_i32 s10, 0x15ff
	s_cbranch_scc1 .LBB0_305
	s_cmpk_gt_i32 s10, 0x17f
	s_cbranch_scc0 .LBB0_342
	s_cmpk_gt_u32 s1, 0x57f
	s_mov_b64 s[36:37], -1
	s_cbranch_scc0 .LBB0_348
	s_cmpk_gt_u32 s1, 0x77f
	s_cbranch_scc0 .LBB0_345
	s_cmpk_gt_u32 s1, 0x127f
	s_cbranch_scc0 .LBB0_363
	s_lshl_b32 s0, s10, 1
	v_readlane_b32 s44, v245, 50
	s_add_i32 s0, s0, 0x1df00
	s_lshl_b32 s4, s1, 5
	v_readlane_b32 s56, v245, 62
	v_readlane_b32 s57, v245, 63
	s_and_b32 s0, s0, 0x1ffc0
	s_and_b32 s8, s4, 0x3e0
	s_mov_b64 s[28:29], 0
	v_readlane_b32 s45, v245, 51
	v_readlane_b32 s46, v245, 52
	v_readlane_b32 s47, v245, 53
	v_readlane_b32 s48, v245, 54
	v_readlane_b32 s49, v245, 55
	v_readlane_b32 s50, v245, 56
	v_readlane_b32 s51, v245, 57
	v_readlane_b32 s52, v245, 58
	v_readlane_b32 s53, v245, 59
	v_readlane_b32 s54, v245, 60
	v_readlane_b32 s55, v245, 61
	v_readlane_b32 s58, v244, 0
	v_readlane_b32 s59, v244, 1
	s_mov_b64 s[30:31], s[56:57]
	s_cbranch_execz .LBB0_364
	s_mov_b64 s[80:81], 0x400
	s_movk_i32 s9, 0xb00
	s_movk_i32 s16, 0x400
	s_mov_b32 s74, s8
	s_mov_b64 s[4:5], s[38:39]
	s_cbranch_execz .LBB0_346
	s_branch .LBB0_347

.LBB0_435:
	s_cmp_lt_i32 s88, 3
	s_cselect_b64 s[6:7], -1, 0
	s_and_b64 s[0:1], s[6:7], s[4:5]
	s_andn2_b64 vcc, exec, s[0:1]
	s_cbranch_vccnz .LBB0_612
	v_readlane_b32 s0, v245, 14
	s_lshl_b32 s36, s0, 3
	v_readlane_b32 s0, v245, 49
	s_add_i32 s1, s36, s0
	s_lshl_b32 s37, s3, 3
	s_cmpk_gt_i32 s1, 0x1ff
	s_branch .LBB0_529
	s_add_i32 s33, s1, 0x1600
	s_cmpk_gt_i32 s1, 0xed7f
	s_cbranch_scc0 .LBB0_442
	v_readlane_b32 s40, v245, 50
	s_cmpk_gt_u32 s33, 0x57f
	v_readlane_b32 s41, v245, 51
	v_readlane_b32 s42, v245, 52
	v_readlane_b32 s43, v245, 53
	v_readlane_b32 s44, v245, 54
	v_readlane_b32 s45, v245, 55
	v_readlane_b32 s46, v245, 56
	v_readlane_b32 s47, v245, 57
	v_readlane_b32 s52, v245, 62
	v_readlane_b32 s53, v245, 63
	v_readlane_b32 s48, v245, 58
	v_readlane_b32 s49, v245, 59
	v_readlane_b32 s50, v245, 60
	v_readlane_b32 s51, v245, 61
	v_readlane_b32 s54, v244, 0
	v_readlane_b32 s55, v244, 1
	s_cbranch_scc0 .LBB0_443
	s_cmpk_gt_u32 s33, 0x77f
	s_cbranch_scc0 .LBB0_444
	s_cmpk_gt_u32 s33, 0x127f
	s_cbranch_scc0 .LBB0_445
	s_lshl_b32 s0, s1, 1
	s_addk_i32 s0, 0x700
	s_lshl_b32 s4, s33, 5
	s_and_b32 s0, s0, 0x1ffc0
	s_and_b32 s38, s4, 0x3e0
	s_add_u32 s4, s34, 0x1400000
	s_addc_u32 s5, s35, 0
	s_mov_b64 s[12:13], 0
	s_mov_b64 s[8:9], 0
	s_mov_b64 s[10:11], s[52:53]
	s_branch .LBB0_446
